# GEMM units: first K iteration peeled, first MFMA of each accumulator uses srcC=0 instead of zeroing 128 accumulator registers per unit
# speedup vs baseline: 1.0025x; 1.0025x over previous
.LBB0_69:
	s_add_i32 m0, s3, 0x18000
	v_lshl_add_u64 v[0:1], v[0:1], 0, s[66:67]
	s_waitcnt vmcnt(4)
	s_barrier
	global_load_lds_dwordx4 v[0:1], off
	v_lshl_add_u64 v[0:1], v[2:3], 0, s[66:67]
	s_add_i32 m0, s3, 0x1a000
	s_add_i32 s30, s3, 0x8000
	global_load_lds_dwordx4 v[0:1], off
	v_lshl_add_u64 v[0:1], v[4:5], 0, s[66:67]
	s_mov_b32 m0, s30
	s_add_i32 s31, s3, 0xa000
	global_load_lds_dwordx4 v[0:1], off
	v_lshl_add_u64 v[0:1], v[6:7], 0, s[66:67]
	s_mov_b32 m0, s31
	v_and_b32_e32 v19, 15, v15
	global_load_lds_dwordx4 v[0:1], off
	s_add_i32 m0, s3, 0x1c000
	v_lshl_add_u64 v[0:1], v[8:9], 0, s[66:67]
	global_load_lds_dwordx4 v[0:1], off
	v_lshl_add_u64 v[0:1], v[10:11], 0, s[66:67]
	s_add_i32 m0, s3, 0x1e000
	v_and_b32_e32 v20, 48, v15
	global_load_lds_dwordx4 v[0:1], off
	v_lshlrev_b32_e32 v19, 6, v19
	v_lshlrev_b32_e32 v15, 2, v15
	s_lshr_b32 s29, s19, 6
	v_or_b32_e32 v21, v19, v20
	s_lshl_b32 s19, s23, 13
	v_and_b32_e32 v15, 32, v15
	v_bitop3_b32 v19, v19, v15, v20 bitop3:0x36
	v_bitop3_b32 v15, v21, s19, v15 bitop3:0xde
	s_lshl_b32 s19, s22, 12
	s_and_b32 s19, s19, 0x3000
	s_add_i32 s34, s29, -2
	s_add_u32 s16, s18, s16
	s_addc_u32 s17, 0, s17
	s_add_u32 s12, s16, s12
	s_addc_u32 s13, s17, s13
	s_add_u32 s12, s12, s25
	s_addc_u32 s13, s13, 0
	s_add_u32 s12, s80, s12
	s_addc_u32 s13, s81, s13
	v_add_u32_e32 v0, v16, v17
	s_add_u32 s12, s12, 0x80
	v_add_lshl_u32 v0, v0, v18, 1
	v_mov_b32_e32 v1, v133
	s_addc_u32 s13, s13, 0
	v_lshl_add_u64 v[130:131], s[12:13], 0, v[0:1]
	v_add_u32_e32 v0, v12, v13
	s_waitcnt vmcnt(6)
	v_add_lshl_u32 v0, v0, v14, 1
	v_lshl_add_u64 v[150:151], s[12:13], 0, v[0:1]
	v_or_b32_e32 v152, s19, v19
	s_mov_b32 s18, 0
	s_mov_b64 s[12:13], 0
	v_add_u32_e32 v153, 0, v15
	s_barrier
	v_add_u32_e32 v166, 0x10000, v152
	ds_read_b128 v[154:157], v166
	ds_read_b128 v[158:161], v166 offset:1024
	ds_read_b128 v[162:165], v166 offset:2048
	ds_read_b128 v[166:169], v166 offset:3072
	s_add_i32 s35, s18, 2
	s_add_u32 s16, s12, 0x100
	s_addc_u32 s17, s13, 0
	s_cmp_lg_u32 s34, s18
	s_cselect_b32 s22, s16, 0
	s_cselect_b32 s23, s17, 0
	s_add_u32 s18, s10, s22
	s_addc_u32 s19, s11, s23
	s_add_i32 s36, 0, 0x10000
	s_add_u32 s22, s8, s22
	s_addc_u32 s23, s9, s23
	v_lshl_add_u64 v[190:191], v[130:131], 0, s[12:13]
	s_add_i32 m0, s3, 0xc000
	ds_read_b128 v[170:173], v153
	ds_read_b128 v[178:181], v153 offset:2048
	ds_read_b128 v[186:189], v153 offset:4096
	ds_read_b128 v[220:223], v153 offset:6144
	ds_read_b128 v[174:177], v153 offset:1024
	ds_read_b128 v[182:185], v153 offset:3072
	ds_read_b128 v[216:219], v153 offset:5120
	ds_read_b128 v[224:227], v153 offset:7168
	global_load_lds_dwordx4 v[190:191], off
	v_lshl_add_u64 v[190:191], v[150:151], 0, s[12:13]
	s_add_i32 m0, s3, 0xe000
	s_nop 0
	global_load_lds_dwordx4 v[190:191], off
	s_waitcnt lgkmcnt(8)
	s_waitcnt vmcnt(10)
	s_barrier
	s_waitcnt lgkmcnt(4)
	s_setprio 1
	v_mfma_f32_16x16x32_bf16 v[124:127], v[154:157], v[170:173], 0
	v_mfma_f32_16x16x32_bf16 v[120:123], v[162:165], v[170:173], 0
	v_mfma_f32_16x16x32_bf16 v[116:119], v[154:157], v[178:181], 0
	v_mfma_f32_16x16x32_bf16 v[108:111], v[162:165], v[178:181], 0
	v_mfma_f32_16x16x32_bf16 v[100:103], v[154:157], v[186:189], 0
	v_mfma_f32_16x16x32_bf16 v[92:95], v[162:165], v[186:189], 0
	v_mfma_f32_16x16x32_bf16 v[84:87], v[154:157], v[220:223], 0
	v_mfma_f32_16x16x32_bf16 v[76:79], v[162:165], v[220:223], 0
	s_waitcnt lgkmcnt(0)
	v_mfma_f32_16x16x32_bf16 v[124:127], v[158:161], v[174:177], v[124:127]
	v_mfma_f32_16x16x32_bf16 v[120:123], v[166:169], v[174:177], v[120:123]
	v_mfma_f32_16x16x32_bf16 v[116:119], v[158:161], v[182:185], v[116:119]
	v_mfma_f32_16x16x32_bf16 v[108:111], v[166:169], v[182:185], v[108:111]
	v_mfma_f32_16x16x32_bf16 v[100:103], v[158:161], v[216:219], v[100:103]
	v_mfma_f32_16x16x32_bf16 v[92:95], v[166:169], v[216:219], v[92:95]
	v_mfma_f32_16x16x32_bf16 v[84:87], v[158:161], v[224:227], v[84:87]
	v_mfma_f32_16x16x32_bf16 v[76:79], v[166:169], v[224:227], v[76:79]
	s_setprio 0
	s_barrier
	s_add_i32 s37, 0, 0x14000
	v_add_u32_e32 v190, s37, v152
	s_add_i32 s12, s36, s26
	ds_read_b128 v[228:231], v190
	ds_read_b128 v[236:239], v190 offset:2048
	ds_read_b128 v[232:235], v190 offset:1024
	ds_read_b128 v[240:243], v190 offset:3072
	v_lshl_add_u64 v[190:191], s[22:23], 0, v[132:133]
	s_mov_b32 m0, s12
	v_lshl_add_u64 v[244:245], s[22:23], 0, v[128:129]
	global_load_lds_dwordx4 v132, s[22:23]
	s_add_i32 m0, s12, 0x2000
	s_nop 0
	global_load_lds_dwordx4 v128, s[22:23]
	s_waitcnt vmcnt(10)
	s_barrier
	s_waitcnt lgkmcnt(2)
	s_setprio 1
	v_mfma_f32_16x16x32_bf16 v[112:115], v[228:231], v[170:173], 0
	v_mfma_f32_16x16x32_bf16 v[104:107], v[236:239], v[170:173], 0
	v_mfma_f32_16x16x32_bf16 v[96:99], v[228:231], v[178:181], 0
	v_mfma_f32_16x16x32_bf16 v[88:91], v[236:239], v[178:181], 0
	v_mfma_f32_16x16x32_bf16 v[80:83], v[228:231], v[186:189], 0
	v_mfma_f32_16x16x32_bf16 v[72:75], v[236:239], v[186:189], 0
	v_mfma_f32_16x16x32_bf16 v[68:71], v[228:231], v[220:223], 0
	v_mfma_f32_16x16x32_bf16 v[64:67], v[236:239], v[220:223], 0
	s_waitcnt lgkmcnt(0)
	v_mfma_f32_16x16x32_bf16 v[112:115], v[232:235], v[174:177], v[112:115]
	v_mfma_f32_16x16x32_bf16 v[104:107], v[240:243], v[174:177], v[104:107]
	v_mfma_f32_16x16x32_bf16 v[96:99], v[232:235], v[182:185], v[96:99]
	v_mfma_f32_16x16x32_bf16 v[88:91], v[240:243], v[182:185], v[88:91]
	v_mfma_f32_16x16x32_bf16 v[80:83], v[232:235], v[216:219], v[80:83]
	v_mfma_f32_16x16x32_bf16 v[72:75], v[240:243], v[216:219], v[72:75]
	v_mfma_f32_16x16x32_bf16 v[68:71], v[232:235], v[224:227], v[68:71]
	v_mfma_f32_16x16x32_bf16 v[64:67], v[240:243], v[224:227], v[64:67]
	s_setprio 0
	s_mov_b32 m0, s3
	s_barrier
	ds_read_b128 v[170:173], v153 offset:16384
	ds_read_b128 v[178:181], v153 offset:18432
	ds_read_b128 v[186:189], v153 offset:20480
	ds_read_b128 v[220:223], v153 offset:22528
	ds_read_b128 v[174:177], v153 offset:17408
	ds_read_b128 v[182:185], v153 offset:19456
	ds_read_b128 v[216:219], v153 offset:21504
	ds_read_b128 v[224:227], v153 offset:23552
	global_load_lds_dwordx4 v132, s[18:19]
	s_mov_b32 m0, s5
	s_nop 0
	global_load_lds_dwordx4 v128, s[18:19]
	s_waitcnt vmcnt(10)
	s_barrier
	s_waitcnt lgkmcnt(4)
	s_setprio 1
	v_mfma_f32_16x16x32_bf16 v[60:63], v[154:157], v[170:173], 0
	v_mfma_f32_16x16x32_bf16 v[56:59], v[162:165], v[170:173], 0
	v_mfma_f32_16x16x32_bf16 v[52:55], v[154:157], v[178:181], 0
	v_mfma_f32_16x16x32_bf16 v[44:47], v[162:165], v[178:181], 0
	v_mfma_f32_16x16x32_bf16 v[36:39], v[154:157], v[186:189], 0
	v_mfma_f32_16x16x32_bf16 v[28:31], v[162:165], v[186:189], 0
	v_mfma_f32_16x16x32_bf16 v[20:23], v[154:157], v[220:223], 0
	v_mfma_f32_16x16x32_bf16 v[12:15], v[162:165], v[220:223], 0
	s_waitcnt lgkmcnt(0)
	v_mfma_f32_16x16x32_bf16 v[60:63], v[158:161], v[174:177], v[60:63]
	v_mfma_f32_16x16x32_bf16 v[56:59], v[166:169], v[174:177], v[56:59]
	v_mfma_f32_16x16x32_bf16 v[52:55], v[158:161], v[182:185], v[52:55]
	v_mfma_f32_16x16x32_bf16 v[44:47], v[166:169], v[182:185], v[44:47]
	v_mfma_f32_16x16x32_bf16 v[36:39], v[158:161], v[216:219], v[36:39]
	v_mfma_f32_16x16x32_bf16 v[28:31], v[166:169], v[216:219], v[28:31]
	v_mfma_f32_16x16x32_bf16 v[20:23], v[158:161], v[224:227], v[20:23]
	v_mfma_f32_16x16x32_bf16 v[12:15], v[166:169], v[224:227], v[12:15]
	s_setprio 0
	s_barrier
	s_add_u32 s12, s22, s25
	s_addc_u32 s13, s23, 0
	s_add_i32 s22, s37, s26
	v_lshl_add_u64 v[250:251], s[12:13], 0, v[132:133]
	s_mov_b32 m0, s22
	v_lshl_add_u64 v[252:253], s[12:13], 0, v[128:129]
	global_load_lds_dwordx4 v132, s[12:13]
	s_add_i32 m0, s22, 0x2000
	s_nop 0
	global_load_lds_dwordx4 v128, s[12:13]
	v_add_u32_e32 v166, 0x18000, v152
	ds_read_b128 v[154:157], v166
	ds_read_b128 v[158:161], v166 offset:1024
	ds_read_b128 v[162:165], v166 offset:2048
	ds_read_b128 v[166:169], v166 offset:3072
	s_waitcnt vmcnt(10)
	s_barrier
	s_setprio 1
	v_mfma_f32_16x16x32_bf16 v[48:51], v[228:231], v[170:173], 0
	v_mfma_f32_16x16x32_bf16 v[40:43], v[236:239], v[170:173], 0
	v_mfma_f32_16x16x32_bf16 v[32:35], v[228:231], v[178:181], 0
	v_mfma_f32_16x16x32_bf16 v[24:27], v[236:239], v[178:181], 0
	v_mfma_f32_16x16x32_bf16 v[16:19], v[228:231], v[186:189], 0
	v_mfma_f32_16x16x32_bf16 v[8:11], v[236:239], v[186:189], 0
	v_mfma_f32_16x16x32_bf16 v[4:7], v[228:231], v[220:223], 0
	v_mfma_f32_16x16x32_bf16 v[0:3], v[236:239], v[220:223], 0
	v_mfma_f32_16x16x32_bf16 v[48:51], v[232:235], v[174:177], v[48:51]
	v_mfma_f32_16x16x32_bf16 v[40:43], v[240:243], v[174:177], v[40:43]
	v_mfma_f32_16x16x32_bf16 v[32:35], v[232:235], v[182:185], v[32:35]
	v_mfma_f32_16x16x32_bf16 v[24:27], v[240:243], v[182:185], v[24:27]
	v_mfma_f32_16x16x32_bf16 v[16:19], v[232:235], v[216:219], v[16:19]
	v_mfma_f32_16x16x32_bf16 v[8:11], v[240:243], v[216:219], v[8:11]
	v_mfma_f32_16x16x32_bf16 v[4:7], v[232:235], v[224:227], v[4:7]
	v_mfma_f32_16x16x32_bf16 v[0:3], v[240:243], v[224:227], v[0:3]
	s_setprio 0
	s_add_i32 s22, 0, 0x18000
	s_barrier
	s_add_u32 s12, s18, s25
	s_addc_u32 s13, s19, 0
	s_mov_b32 m0, s27
	ds_read_b128 v[170:173], v153 offset:32768
	ds_read_b128 v[178:181], v153 offset:34816
	ds_read_b128 v[186:189], v153 offset:36864
	ds_read_b128 v[220:223], v153 offset:38912
	ds_read_b128 v[174:177], v153 offset:33792
	ds_read_b128 v[182:185], v153 offset:35840
	ds_read_b128 v[216:219], v153 offset:37888
	ds_read_b128 v[224:227], v153 offset:39936
	global_load_lds_dwordx4 v132, s[12:13]
	s_mov_b32 m0, s28
	s_nop 0
	global_load_lds_dwordx4 v128, s[12:13]
	s_waitcnt lgkmcnt(8)
	s_waitcnt vmcnt(10)
	s_barrier
	s_waitcnt lgkmcnt(4)
	s_setprio 1
	v_mfma_f32_16x16x32_bf16 v[124:127], v[154:157], v[170:173], v[124:127]
	v_mfma_f32_16x16x32_bf16 v[120:123], v[162:165], v[170:173], v[120:123]
	v_mfma_f32_16x16x32_bf16 v[116:119], v[154:157], v[178:181], v[116:119]
	v_mfma_f32_16x16x32_bf16 v[108:111], v[162:165], v[178:181], v[108:111]
	v_mfma_f32_16x16x32_bf16 v[100:103], v[154:157], v[186:189], v[100:103]
	v_mfma_f32_16x16x32_bf16 v[92:95], v[162:165], v[186:189], v[92:95]
	v_mfma_f32_16x16x32_bf16 v[84:87], v[154:157], v[220:223], v[84:87]
	v_mfma_f32_16x16x32_bf16 v[76:79], v[162:165], v[220:223], v[76:79]
	s_waitcnt lgkmcnt(0)
	v_mfma_f32_16x16x32_bf16 v[124:127], v[158:161], v[174:177], v[124:127]
	v_mfma_f32_16x16x32_bf16 v[120:123], v[166:169], v[174:177], v[120:123]
	v_mfma_f32_16x16x32_bf16 v[116:119], v[158:161], v[182:185], v[116:119]
	v_mfma_f32_16x16x32_bf16 v[108:111], v[166:169], v[182:185], v[108:111]
	v_mfma_f32_16x16x32_bf16 v[100:103], v[158:161], v[216:219], v[100:103]
	v_mfma_f32_16x16x32_bf16 v[92:95], v[166:169], v[216:219], v[92:95]
	v_mfma_f32_16x16x32_bf16 v[84:87], v[158:161], v[224:227], v[84:87]
	v_mfma_f32_16x16x32_bf16 v[76:79], v[166:169], v[224:227], v[76:79]
	s_setprio 0
	s_barrier
	s_add_i32 s12, 0, 0x1c000
	s_add_i32 s13, s22, s26
	v_add_u32_e32 v200, s12, v152
	v_lshl_add_u64 v[190:191], v[190:191], 0, s[66:67]
	s_mov_b32 m0, s13
	ds_read_b128 v[228:231], v200
	ds_read_b128 v[236:239], v200 offset:2048
	ds_read_b128 v[232:235], v200 offset:1024
	ds_read_b128 v[240:243], v200 offset:3072
	global_load_lds_dwordx4 v[190:191], off
	v_lshl_add_u64 v[190:191], v[244:245], 0, s[66:67]
	s_add_i32 m0, s13, 0x2000
	s_nop 0
	global_load_lds_dwordx4 v[190:191], off
	s_waitcnt vmcnt(10)
	s_barrier
	s_waitcnt lgkmcnt(2)
	s_setprio 1
	v_mfma_f32_16x16x32_bf16 v[112:115], v[228:231], v[170:173], v[112:115]
	v_mfma_f32_16x16x32_bf16 v[104:107], v[236:239], v[170:173], v[104:107]
	v_mfma_f32_16x16x32_bf16 v[96:99], v[228:231], v[178:181], v[96:99]
	v_mfma_f32_16x16x32_bf16 v[88:91], v[236:239], v[178:181], v[88:91]
	v_mfma_f32_16x16x32_bf16 v[80:83], v[228:231], v[186:189], v[80:83]
	v_mfma_f32_16x16x32_bf16 v[72:75], v[236:239], v[186:189], v[72:75]
	v_mfma_f32_16x16x32_bf16 v[68:71], v[228:231], v[220:223], v[68:71]
	v_mfma_f32_16x16x32_bf16 v[64:67], v[236:239], v[220:223], v[64:67]
	s_waitcnt lgkmcnt(0)
	v_mfma_f32_16x16x32_bf16 v[112:115], v[232:235], v[174:177], v[112:115]
	v_mfma_f32_16x16x32_bf16 v[104:107], v[240:243], v[174:177], v[104:107]
	v_mfma_f32_16x16x32_bf16 v[96:99], v[232:235], v[182:185], v[96:99]
	v_mfma_f32_16x16x32_bf16 v[88:91], v[240:243], v[182:185], v[88:91]
	v_mfma_f32_16x16x32_bf16 v[80:83], v[232:235], v[216:219], v[80:83]
	v_mfma_f32_16x16x32_bf16 v[72:75], v[240:243], v[216:219], v[72:75]
	v_mfma_f32_16x16x32_bf16 v[68:71], v[232:235], v[224:227], v[68:71]
	v_mfma_f32_16x16x32_bf16 v[64:67], v[240:243], v[224:227], v[64:67]
	s_setprio 0
	s_mov_b32 m0, s30
	s_barrier
	ds_read_b128 v[170:173], v153 offset:49152
	ds_read_b128 v[178:181], v153 offset:51200
	ds_read_b128 v[186:189], v153 offset:53248
	ds_read_b128 v[220:223], v153 offset:55296
	ds_read_b128 v[174:177], v153 offset:50176
	ds_read_b128 v[182:185], v153 offset:52224
	ds_read_b128 v[216:219], v153 offset:54272
	ds_read_b128 v[224:227], v153 offset:56320
	s_add_u32 s98, s18, 0x80
	s_addc_u32 s99, s19, 0
	global_load_lds_dwordx4 v132, s[98:99]
	s_mov_b32 m0, s31
	s_nop 0
	global_load_lds_dwordx4 v128, s[98:99]
	s_waitcnt vmcnt(10)
	s_barrier
	s_waitcnt lgkmcnt(4)
	s_setprio 1
	v_mfma_f32_16x16x32_bf16 v[60:63], v[154:157], v[170:173], v[60:63]
	v_mfma_f32_16x16x32_bf16 v[56:59], v[162:165], v[170:173], v[56:59]
	v_mfma_f32_16x16x32_bf16 v[52:55], v[154:157], v[178:181], v[52:55]
	v_mfma_f32_16x16x32_bf16 v[44:47], v[162:165], v[178:181], v[44:47]
	v_mfma_f32_16x16x32_bf16 v[36:39], v[154:157], v[186:189], v[36:39]
	v_mfma_f32_16x16x32_bf16 v[28:31], v[162:165], v[186:189], v[28:31]
	v_mfma_f32_16x16x32_bf16 v[20:23], v[154:157], v[220:223], v[20:23]
	v_mfma_f32_16x16x32_bf16 v[12:15], v[162:165], v[220:223], v[12:15]
	s_waitcnt lgkmcnt(0)
	v_mfma_f32_16x16x32_bf16 v[60:63], v[158:161], v[174:177], v[60:63]
	v_mfma_f32_16x16x32_bf16 v[56:59], v[166:169], v[174:177], v[56:59]
	v_mfma_f32_16x16x32_bf16 v[52:55], v[158:161], v[182:185], v[52:55]
	v_mfma_f32_16x16x32_bf16 v[44:47], v[166:169], v[182:185], v[44:47]
	v_mfma_f32_16x16x32_bf16 v[36:39], v[158:161], v[216:219], v[36:39]
	v_mfma_f32_16x16x32_bf16 v[28:31], v[166:169], v[216:219], v[28:31]
	v_mfma_f32_16x16x32_bf16 v[20:23], v[158:161], v[224:227], v[20:23]
	v_mfma_f32_16x16x32_bf16 v[12:15], v[166:169], v[224:227], v[12:15]
	s_setprio 0
	s_barrier
	s_add_i32 s12, s12, s26
	v_lshl_add_u64 v[154:155], v[250:251], 0, s[66:67]
	s_mov_b32 m0, s12
	s_nop 0
	global_load_lds_dwordx4 v[154:155], off
	v_lshl_add_u64 v[154:155], v[252:253], 0, s[66:67]
	s_add_i32 m0, s12, 0x2000
	s_nop 0
	global_load_lds_dwordx4 v[154:155], off
	v_add_u32_e32 v166, 0x10000, v152
	ds_read_b128 v[154:157], v166
	ds_read_b128 v[158:161], v166 offset:1024
	ds_read_b128 v[162:165], v166 offset:2048
	ds_read_b128 v[166:169], v166 offset:3072
	s_waitcnt vmcnt(10)
	s_barrier
	s_setprio 1
	v_mfma_f32_16x16x32_bf16 v[48:51], v[228:231], v[170:173], v[48:51]
	v_mfma_f32_16x16x32_bf16 v[40:43], v[236:239], v[170:173], v[40:43]
	v_mfma_f32_16x16x32_bf16 v[32:35], v[228:231], v[178:181], v[32:35]
	v_mfma_f32_16x16x32_bf16 v[24:27], v[236:239], v[178:181], v[24:27]
	v_mfma_f32_16x16x32_bf16 v[16:19], v[228:231], v[186:189], v[16:19]
	v_mfma_f32_16x16x32_bf16 v[8:11], v[236:239], v[186:189], v[8:11]
	v_mfma_f32_16x16x32_bf16 v[4:7], v[228:231], v[220:223], v[4:7]
	v_mfma_f32_16x16x32_bf16 v[0:3], v[236:239], v[220:223], v[0:3]
	v_mfma_f32_16x16x32_bf16 v[48:51], v[232:235], v[174:177], v[48:51]
	v_mfma_f32_16x16x32_bf16 v[40:43], v[240:243], v[174:177], v[40:43]
	v_mfma_f32_16x16x32_bf16 v[32:35], v[232:235], v[182:185], v[32:35]
	v_mfma_f32_16x16x32_bf16 v[24:27], v[240:243], v[182:185], v[24:27]
	v_mfma_f32_16x16x32_bf16 v[16:19], v[232:235], v[216:219], v[16:19]
	v_mfma_f32_16x16x32_bf16 v[8:11], v[240:243], v[216:219], v[8:11]
	v_mfma_f32_16x16x32_bf16 v[4:7], v[232:235], v[224:227], v[4:7]
	v_mfma_f32_16x16x32_bf16 v[0:3], v[240:243], v[224:227], v[0:3]
	s_setprio 0
	s_cmp_ge_u32 s35, s29
	s_mov_b64 s[12:13], s[16:17]
	s_mov_b32 s18, s35
	s_barrier

.LBB0_144:
	s_ashr_i32 s19, s18, 31
	v_cmp_lt_i64_e32 vcc, s[10:11], v[140:141]
	s_lshl_b64 s[10:11], s[18:19], 19
	s_add_u32 s22, s86, s10
	s_addc_u32 s23, s87, s11
	s_and_b64 s[10:11], vcc, exec
	s_cselect_b32 s9, s23, s3
	s_cselect_b32 s12, s22, s2
	s_cmp_eq_u32 s16, 5
	s_cselect_b32 s17, 7, s16
	s_cmp_eq_u32 s16, 7
	s_cselect_b32 s16, 5, s17
	s_ashr_i32 s17, s16, 31
	s_lshl_b64 s[10:11], s[16:17], 19
	s_add_u32 s24, s41, s10
	s_addc_u32 s25, s14, s11
	s_and_b64 s[10:11], vcc, exec
	s_cselect_b32 s13, s25, s7
	s_cselect_b32 s17, s24, s6
	s_add_u32 s2, s2, 0x40080
	s_addc_u32 s3, s3, 0
	s_add_u32 s19, s6, 0x100
	s_addc_u32 s27, s7, 0
	s_waitcnt lgkmcnt(0)
	s_mov_b32 s28, -2
	v_add_u32_e32 v166, 0x10000, v215
	ds_read_b128 v[128:131], v166
	ds_read_b128 v[158:161], v166 offset:1024
	ds_read_b128 v[162:165], v166 offset:2048
	ds_read_b128 v[166:169], v166 offset:3072
	s_add_u32 s6, s2, 0xfffc0080
	s_addc_u32 s7, s3, -1
	s_add_i32 s29, 0, 0x10000
	s_cmp_eq_u32 s28, 12
	s_cselect_b32 s11, s9, s7
	s_cselect_b32 s10, s12, s6
	s_cselect_b32 s7, s13, s27
	s_cselect_b32 s6, s17, s19
	s_add_i32 m0, s50, 0xc000
	ds_read_b128 v[170:173], v216
	ds_read_b128 v[178:181], v216 offset:2048
	ds_read_b128 v[186:189], v216 offset:4096
	ds_read_b128 v[222:225], v216 offset:6144
	ds_read_b128 v[174:177], v216 offset:1024
	ds_read_b128 v[182:185], v216 offset:3072
	ds_read_b128 v[218:221], v216 offset:5120
	ds_read_b128 v[226:229], v216 offset:7168
	global_load_lds_dwordx4 v154, s[2:3]
	s_add_i32 m0, s50, 0xe000
	s_nop 0
	global_load_lds_dwordx4 v156, s[2:3]
	s_waitcnt lgkmcnt(8)
	s_waitcnt vmcnt(10)
	s_barrier
	s_waitcnt lgkmcnt(4)
	s_setprio 1
	v_mfma_f32_16x16x32_bf16 v[124:127], v[128:131], v[170:173], 0
	v_mfma_f32_16x16x32_bf16 v[120:123], v[162:165], v[170:173], 0
	v_mfma_f32_16x16x32_bf16 v[108:111], v[128:131], v[178:181], 0
	v_mfma_f32_16x16x32_bf16 v[104:107], v[162:165], v[178:181], 0
	v_mfma_f32_16x16x32_bf16 v[92:95], v[128:131], v[186:189], 0
	v_mfma_f32_16x16x32_bf16 v[88:91], v[162:165], v[186:189], 0
	v_mfma_f32_16x16x32_bf16 v[76:79], v[128:131], v[222:225], 0
	v_mfma_f32_16x16x32_bf16 v[72:75], v[162:165], v[222:225], 0
	s_waitcnt lgkmcnt(0)
	v_mfma_f32_16x16x32_bf16 v[124:127], v[158:161], v[174:177], v[124:127]
	v_mfma_f32_16x16x32_bf16 v[120:123], v[166:169], v[174:177], v[120:123]
	v_mfma_f32_16x16x32_bf16 v[108:111], v[158:161], v[182:185], v[108:111]
	v_mfma_f32_16x16x32_bf16 v[104:107], v[166:169], v[182:185], v[104:107]
	v_mfma_f32_16x16x32_bf16 v[92:95], v[158:161], v[218:221], v[92:95]
	v_mfma_f32_16x16x32_bf16 v[88:91], v[166:169], v[218:221], v[88:91]
	v_mfma_f32_16x16x32_bf16 v[76:79], v[158:161], v[226:229], v[76:79]
	v_mfma_f32_16x16x32_bf16 v[72:75], v[166:169], v[226:229], v[72:75]
	s_setprio 0
	s_barrier
	s_add_i32 s34, 0, 0x14000
	s_add_i32 s29, s29, s15
	v_add_u32_e32 v132, s34, v215
	s_mov_b32 m0, s29
	ds_read_b128 v[230:233], v132
	ds_read_b128 v[238:241], v132 offset:2048
	ds_read_b128 v[234:237], v132 offset:1024
	ds_read_b128 v[242:245], v132 offset:3072
	global_load_lds_dwordx4 v150, s[6:7]
	s_add_i32 m0, s29, 0x2000
	s_nop 0
	global_load_lds_dwordx4 v152, s[6:7]
	s_waitcnt vmcnt(10)
	s_barrier
	s_waitcnt lgkmcnt(2)
	s_setprio 1
	v_mfma_f32_16x16x32_bf16 v[116:119], v[230:233], v[170:173], 0
	v_mfma_f32_16x16x32_bf16 v[112:115], v[238:241], v[170:173], 0
	v_mfma_f32_16x16x32_bf16 v[100:103], v[230:233], v[178:181], 0
	v_mfma_f32_16x16x32_bf16 v[96:99], v[238:241], v[178:181], 0
	v_mfma_f32_16x16x32_bf16 v[84:87], v[230:233], v[186:189], 0
	v_mfma_f32_16x16x32_bf16 v[80:83], v[238:241], v[186:189], 0
	v_mfma_f32_16x16x32_bf16 v[68:71], v[230:233], v[222:225], 0
	v_mfma_f32_16x16x32_bf16 v[64:67], v[238:241], v[222:225], 0
	s_waitcnt lgkmcnt(0)
	v_mfma_f32_16x16x32_bf16 v[116:119], v[234:237], v[174:177], v[116:119]
	v_mfma_f32_16x16x32_bf16 v[112:115], v[242:245], v[174:177], v[112:115]
	v_mfma_f32_16x16x32_bf16 v[100:103], v[234:237], v[182:185], v[100:103]
	v_mfma_f32_16x16x32_bf16 v[96:99], v[242:245], v[182:185], v[96:99]
	v_mfma_f32_16x16x32_bf16 v[84:87], v[234:237], v[218:221], v[84:87]
	v_mfma_f32_16x16x32_bf16 v[80:83], v[242:245], v[218:221], v[80:83]
	v_mfma_f32_16x16x32_bf16 v[68:71], v[234:237], v[226:229], v[68:71]
	v_mfma_f32_16x16x32_bf16 v[64:67], v[242:245], v[226:229], v[64:67]
	s_setprio 0
	s_mov_b32 m0, s50
	v_lshl_add_u64 v[248:249], s[10:11], 0, v[150:151]
	s_barrier
	ds_read_b128 v[170:173], v216 offset:16384
	ds_read_b128 v[178:181], v216 offset:18432
	ds_read_b128 v[186:189], v216 offset:20480
	ds_read_b128 v[222:225], v216 offset:22528
	ds_read_b128 v[174:177], v216 offset:17408
	ds_read_b128 v[182:185], v216 offset:19456
	ds_read_b128 v[218:221], v216 offset:21504
	ds_read_b128 v[226:229], v216 offset:23552
	global_load_lds_dwordx4 v150, s[10:11]
	v_lshl_add_u64 v[250:251], s[10:11], 0, v[152:153]
	s_mov_b32 m0, s51
	s_nop 0
	global_load_lds_dwordx4 v152, s[10:11]
	s_waitcnt vmcnt(10)
	s_barrier
	s_waitcnt lgkmcnt(4)
	s_setprio 1
	v_mfma_f32_16x16x32_bf16 v[60:63], v[128:131], v[170:173], 0
	v_mfma_f32_16x16x32_bf16 v[56:59], v[162:165], v[170:173], 0
	v_mfma_f32_16x16x32_bf16 v[44:47], v[128:131], v[178:181], 0
	v_mfma_f32_16x16x32_bf16 v[40:43], v[162:165], v[178:181], 0
	v_mfma_f32_16x16x32_bf16 v[28:31], v[128:131], v[186:189], 0
	v_mfma_f32_16x16x32_bf16 v[24:27], v[162:165], v[186:189], 0
	v_mfma_f32_16x16x32_bf16 v[12:15], v[128:131], v[222:225], 0
	v_mfma_f32_16x16x32_bf16 v[8:11], v[162:165], v[222:225], 0
	s_waitcnt lgkmcnt(0)
	v_mfma_f32_16x16x32_bf16 v[60:63], v[158:161], v[174:177], v[60:63]
	v_mfma_f32_16x16x32_bf16 v[56:59], v[166:169], v[174:177], v[56:59]
	v_mfma_f32_16x16x32_bf16 v[44:47], v[158:161], v[182:185], v[44:47]
	v_mfma_f32_16x16x32_bf16 v[40:43], v[166:169], v[182:185], v[40:43]
	v_mfma_f32_16x16x32_bf16 v[28:31], v[158:161], v[218:221], v[28:31]
	v_mfma_f32_16x16x32_bf16 v[24:27], v[166:169], v[218:221], v[24:27]
	v_mfma_f32_16x16x32_bf16 v[12:15], v[158:161], v[226:229], v[12:15]
	v_mfma_f32_16x16x32_bf16 v[8:11], v[166:169], v[226:229], v[8:11]
	s_setprio 0
	s_barrier
	s_add_u32 s30, s6, 0x40000
	s_addc_u32 s31, s7, 0
	s_add_i32 s29, s34, s15
	s_mov_b32 m0, s29
	s_nop 0
	global_load_lds_dwordx4 v150, s[30:31]
	s_add_i32 m0, s29, 0x2000
	s_nop 0
	global_load_lds_dwordx4 v152, s[30:31]
	v_add_u32_e32 v166, 0x18000, v215
	ds_read_b128 v[128:131], v166
	ds_read_b128 v[158:161], v166 offset:1024
	ds_read_b128 v[162:165], v166 offset:2048
	ds_read_b128 v[166:169], v166 offset:3072
	s_waitcnt vmcnt(10)
	s_barrier
	s_setprio 1
	v_mfma_f32_16x16x32_bf16 v[52:55], v[230:233], v[170:173], 0
	v_mfma_f32_16x16x32_bf16 v[48:51], v[238:241], v[170:173], 0
	v_mfma_f32_16x16x32_bf16 v[36:39], v[230:233], v[178:181], 0
	v_mfma_f32_16x16x32_bf16 v[32:35], v[238:241], v[178:181], 0
	v_mfma_f32_16x16x32_bf16 v[20:23], v[230:233], v[186:189], 0
	v_mfma_f32_16x16x32_bf16 v[16:19], v[238:241], v[186:189], 0
	v_mfma_f32_16x16x32_bf16 v[4:7], v[230:233], v[222:225], 0
	v_mfma_f32_16x16x32_bf16 v[0:3], v[238:241], v[222:225], 0
	v_mfma_f32_16x16x32_bf16 v[52:55], v[234:237], v[174:177], v[52:55]
	v_mfma_f32_16x16x32_bf16 v[48:51], v[242:245], v[174:177], v[48:51]
	v_mfma_f32_16x16x32_bf16 v[36:39], v[234:237], v[182:185], v[36:39]
	v_mfma_f32_16x16x32_bf16 v[32:35], v[242:245], v[182:185], v[32:35]
	v_mfma_f32_16x16x32_bf16 v[20:23], v[234:237], v[218:221], v[20:23]
	v_mfma_f32_16x16x32_bf16 v[16:19], v[242:245], v[218:221], v[16:19]
	v_mfma_f32_16x16x32_bf16 v[4:7], v[234:237], v[226:229], v[4:7]
	v_mfma_f32_16x16x32_bf16 v[0:3], v[242:245], v[226:229], v[0:3]
	s_setprio 0
	s_add_i32 s29, 0, 0x18000
	s_barrier
	s_add_u32 s10, s10, 0x40000
	s_addc_u32 s11, s11, 0
	s_mov_b32 m0, s36
	ds_read_b128 v[170:173], v216 offset:32768
	ds_read_b128 v[178:181], v216 offset:34816
	ds_read_b128 v[186:189], v216 offset:36864
	ds_read_b128 v[222:225], v216 offset:38912
	ds_read_b128 v[174:177], v216 offset:33792
	ds_read_b128 v[182:185], v216 offset:35840
	ds_read_b128 v[218:221], v216 offset:37888
	ds_read_b128 v[226:229], v216 offset:39936
	global_load_lds_dwordx4 v150, s[10:11]
	s_mov_b32 m0, s37
	s_nop 0
	global_load_lds_dwordx4 v152, s[10:11]
	s_waitcnt lgkmcnt(8)
	s_waitcnt vmcnt(10)
	s_barrier
	s_waitcnt lgkmcnt(4)
	s_setprio 1
	v_mfma_f32_16x16x32_bf16 v[124:127], v[128:131], v[170:173], v[124:127]
	v_mfma_f32_16x16x32_bf16 v[120:123], v[162:165], v[170:173], v[120:123]
	v_mfma_f32_16x16x32_bf16 v[108:111], v[128:131], v[178:181], v[108:111]
	v_mfma_f32_16x16x32_bf16 v[104:107], v[162:165], v[178:181], v[104:107]
	v_mfma_f32_16x16x32_bf16 v[92:95], v[128:131], v[186:189], v[92:95]
	v_mfma_f32_16x16x32_bf16 v[88:91], v[162:165], v[186:189], v[88:91]
	v_mfma_f32_16x16x32_bf16 v[76:79], v[128:131], v[222:225], v[76:79]
	v_mfma_f32_16x16x32_bf16 v[72:75], v[162:165], v[222:225], v[72:75]
	s_waitcnt lgkmcnt(0)
	v_mfma_f32_16x16x32_bf16 v[124:127], v[158:161], v[174:177], v[124:127]
	v_mfma_f32_16x16x32_bf16 v[120:123], v[166:169], v[174:177], v[120:123]
	v_mfma_f32_16x16x32_bf16 v[108:111], v[158:161], v[182:185], v[108:111]
	v_mfma_f32_16x16x32_bf16 v[104:107], v[166:169], v[182:185], v[104:107]
	v_mfma_f32_16x16x32_bf16 v[92:95], v[158:161], v[218:221], v[92:95]
	v_mfma_f32_16x16x32_bf16 v[88:91], v[166:169], v[218:221], v[88:91]
	v_mfma_f32_16x16x32_bf16 v[76:79], v[158:161], v[226:229], v[76:79]
	v_mfma_f32_16x16x32_bf16 v[72:75], v[166:169], v[226:229], v[72:75]
	s_setprio 0
	s_barrier
	s_add_i32 s10, 0, 0x1c000
	s_add_i32 s11, s29, s15
	v_add_u32_e32 v132, s10, v215
	s_mov_b32 m0, s11
	ds_read_b128 v[230:233], v132
	ds_read_b128 v[238:241], v132 offset:2048
	ds_read_b128 v[234:237], v132 offset:1024
	ds_read_b128 v[242:245], v132 offset:3072
	s_add_u32 s98, s6, 0x80
	s_addc_u32 s99, s7, 0
	global_load_lds_dwordx4 v150, s[98:99]
	s_add_i32 m0, s11, 0x2000
	s_nop 0
	global_load_lds_dwordx4 v152, s[98:99]
	s_waitcnt vmcnt(10)
	s_barrier
	s_waitcnt lgkmcnt(2)
	s_setprio 1
	v_mfma_f32_16x16x32_bf16 v[116:119], v[230:233], v[170:173], v[116:119]
	v_mfma_f32_16x16x32_bf16 v[112:115], v[238:241], v[170:173], v[112:115]
	v_mfma_f32_16x16x32_bf16 v[100:103], v[230:233], v[178:181], v[100:103]
	v_mfma_f32_16x16x32_bf16 v[96:99], v[238:241], v[178:181], v[96:99]
	v_mfma_f32_16x16x32_bf16 v[84:87], v[230:233], v[186:189], v[84:87]
	v_mfma_f32_16x16x32_bf16 v[80:83], v[238:241], v[186:189], v[80:83]
	v_mfma_f32_16x16x32_bf16 v[68:71], v[230:233], v[222:225], v[68:71]
	v_mfma_f32_16x16x32_bf16 v[64:67], v[238:241], v[222:225], v[64:67]
	s_waitcnt lgkmcnt(0)
	v_mfma_f32_16x16x32_bf16 v[116:119], v[234:237], v[174:177], v[116:119]
	v_mfma_f32_16x16x32_bf16 v[112:115], v[242:245], v[174:177], v[112:115]
	v_mfma_f32_16x16x32_bf16 v[100:103], v[234:237], v[182:185], v[100:103]
	v_mfma_f32_16x16x32_bf16 v[96:99], v[242:245], v[182:185], v[96:99]
	v_mfma_f32_16x16x32_bf16 v[84:87], v[234:237], v[218:221], v[84:87]
	v_mfma_f32_16x16x32_bf16 v[80:83], v[242:245], v[218:221], v[80:83]
	v_mfma_f32_16x16x32_bf16 v[68:71], v[234:237], v[226:229], v[68:71]
	v_mfma_f32_16x16x32_bf16 v[64:67], v[242:245], v[226:229], v[64:67]
	s_setprio 0
	s_mov_b32 m0, s52
	v_lshl_add_u64 v[190:191], v[248:249], 0, s[66:67]
	s_barrier
	ds_read_b128 v[170:173], v216 offset:49152
	ds_read_b128 v[178:181], v216 offset:51200
	ds_read_b128 v[186:189], v216 offset:53248
	ds_read_b128 v[222:225], v216 offset:55296
	ds_read_b128 v[174:177], v216 offset:50176
	ds_read_b128 v[182:185], v216 offset:52224
	ds_read_b128 v[218:221], v216 offset:54272
	ds_read_b128 v[226:229], v216 offset:56320
	global_load_lds_dwordx4 v[190:191], off
	v_lshl_add_u64 v[190:191], v[250:251], 0, s[66:67]
	s_mov_b32 m0, s53
	s_nop 0
	global_load_lds_dwordx4 v[190:191], off
	s_waitcnt vmcnt(10)
	s_barrier
	s_waitcnt lgkmcnt(4)
	s_setprio 1
	v_mfma_f32_16x16x32_bf16 v[60:63], v[128:131], v[170:173], v[60:63]
	v_mfma_f32_16x16x32_bf16 v[56:59], v[162:165], v[170:173], v[56:59]
	v_mfma_f32_16x16x32_bf16 v[44:47], v[128:131], v[178:181], v[44:47]
	v_mfma_f32_16x16x32_bf16 v[40:43], v[162:165], v[178:181], v[40:43]
	v_mfma_f32_16x16x32_bf16 v[28:31], v[128:131], v[186:189], v[28:31]
	v_mfma_f32_16x16x32_bf16 v[24:27], v[162:165], v[186:189], v[24:27]
	v_mfma_f32_16x16x32_bf16 v[12:15], v[128:131], v[222:225], v[12:15]
	v_mfma_f32_16x16x32_bf16 v[8:11], v[162:165], v[222:225], v[8:11]
	s_waitcnt lgkmcnt(0)
	v_mfma_f32_16x16x32_bf16 v[60:63], v[158:161], v[174:177], v[60:63]
	v_mfma_f32_16x16x32_bf16 v[56:59], v[166:169], v[174:177], v[56:59]
	v_mfma_f32_16x16x32_bf16 v[44:47], v[158:161], v[182:185], v[44:47]
	v_mfma_f32_16x16x32_bf16 v[40:43], v[166:169], v[182:185], v[40:43]
	v_mfma_f32_16x16x32_bf16 v[28:31], v[158:161], v[218:221], v[28:31]
	v_mfma_f32_16x16x32_bf16 v[24:27], v[166:169], v[218:221], v[24:27]
	v_mfma_f32_16x16x32_bf16 v[12:15], v[158:161], v[226:229], v[12:15]
	v_mfma_f32_16x16x32_bf16 v[8:11], v[166:169], v[226:229], v[8:11]
	s_setprio 0
	s_barrier
	s_add_u32 s6, s6, 0x40080
	s_addc_u32 s7, s7, 0
	s_add_i32 s10, s10, s15
	s_mov_b32 m0, s10
	s_nop 0
	global_load_lds_dwordx4 v150, s[6:7]
	s_add_i32 m0, s10, 0x2000
	s_nop 0
	global_load_lds_dwordx4 v152, s[6:7]
	v_add_u32_e32 v166, 0x10000, v215
	ds_read_b128 v[128:131], v166
	ds_read_b128 v[158:161], v166 offset:1024
	ds_read_b128 v[162:165], v166 offset:2048
	ds_read_b128 v[166:169], v166 offset:3072
	s_waitcnt vmcnt(10)
	s_barrier
	s_setprio 1
	v_mfma_f32_16x16x32_bf16 v[52:55], v[230:233], v[170:173], v[52:55]
	v_mfma_f32_16x16x32_bf16 v[48:51], v[238:241], v[170:173], v[48:51]
	v_mfma_f32_16x16x32_bf16 v[36:39], v[230:233], v[178:181], v[36:39]
	v_mfma_f32_16x16x32_bf16 v[32:35], v[238:241], v[178:181], v[32:35]
	v_mfma_f32_16x16x32_bf16 v[20:23], v[230:233], v[186:189], v[20:23]
	v_mfma_f32_16x16x32_bf16 v[16:19], v[238:241], v[186:189], v[16:19]
	v_mfma_f32_16x16x32_bf16 v[4:7], v[230:233], v[222:225], v[4:7]
	v_mfma_f32_16x16x32_bf16 v[0:3], v[238:241], v[222:225], v[0:3]
	v_mfma_f32_16x16x32_bf16 v[52:55], v[234:237], v[174:177], v[52:55]
	v_mfma_f32_16x16x32_bf16 v[48:51], v[242:245], v[174:177], v[48:51]
	v_mfma_f32_16x16x32_bf16 v[36:39], v[234:237], v[182:185], v[36:39]
	v_mfma_f32_16x16x32_bf16 v[32:35], v[242:245], v[182:185], v[32:35]
	v_mfma_f32_16x16x32_bf16 v[20:23], v[234:237], v[218:221], v[20:23]
	v_mfma_f32_16x16x32_bf16 v[16:19], v[242:245], v[218:221], v[16:19]
	v_mfma_f32_16x16x32_bf16 v[4:7], v[234:237], v[226:229], v[4:7]
	v_mfma_f32_16x16x32_bf16 v[0:3], v[242:245], v[226:229], v[0:3]
	s_setprio 0
	s_add_i32 s28, s28, 2
	s_add_u32 s2, s2, 0x100
	s_addc_u32 s3, s3, 0
	s_add_u32 s19, s19, 0x100
	s_addc_u32 s27, s27, 0
	s_cmp_gt_u32 s28, 13
	s_barrier

.LBB0_1103:
	s_ashr_i32 s9, s8, 31
	v_cmp_lt_i64_e32 vcc, s[10:11], v[144:145]
	s_lshl_b64 s[10:11], s[8:9], 19
	s_add_u32 s10, s15, s10
	s_addc_u32 s11, s26, s11
	s_and_b64 s[12:13], vcc, exec
	s_cselect_b32 s9, s11, s19
	s_cselect_b32 s42, s10, s18
	s_ashr_i32 s7, s6, 31
	s_lshl_b64 s[12:13], s[6:7], 19
	s_add_u32 s12, s27, s12
	s_addc_u32 s13, s28, s13
	s_and_b64 s[24:25], vcc, exec
	s_cselect_b32 s7, s13, s23
	s_cselect_b32 s43, s12, s22
	s_add_u32 s18, s18, 0x40080
	s_addc_u32 s19, s19, 0
	s_add_u32 s44, s22, 0x100
	s_addc_u32 s45, s23, 0
	s_mov_b32 s46, -2
	v_add_u32_e32 v168, 0x10000, v154
	ds_read_b128 v[156:159], v168
	ds_read_b128 v[160:163], v168 offset:1024
	ds_read_b128 v[164:167], v168 offset:2048
	ds_read_b128 v[168:171], v168 offset:3072
	s_add_u32 s22, s18, 0xfffc0080
	s_addc_u32 s23, s19, -1
	s_add_i32 s47, 0, 0x10000
	s_cmp_eq_u32 s46, 12
	s_cselect_b32 s25, s9, s23
	s_cselect_b32 s24, s42, s22
	s_cselect_b32 s23, s7, s45
	s_cselect_b32 s22, s43, s44
	s_add_i32 m0, s17, 0xc000
	ds_read_b128 v[172:175], v155
	ds_read_b128 v[180:183], v155 offset:2048
	ds_read_b128 v[188:191], v155 offset:4096
	ds_read_b128 v[220:223], v155 offset:6144
	ds_read_b128 v[176:179], v155 offset:1024
	ds_read_b128 v[184:187], v155 offset:3072
	ds_read_b128 v[216:219], v155 offset:5120
	ds_read_b128 v[224:227], v155 offset:7168
	global_load_lds_dwordx4 v130, s[18:19]
	s_add_i32 m0, s17, 0xe000
	s_nop 0
	global_load_lds_dwordx4 v150, s[18:19]
	s_waitcnt lgkmcnt(8)
	s_waitcnt vmcnt(10)
	s_barrier
	s_waitcnt lgkmcnt(4)
	s_setprio 1
	v_mfma_f32_16x16x32_bf16 v[124:127], v[156:159], v[172:175], 0
	v_mfma_f32_16x16x32_bf16 v[120:123], v[164:167], v[172:175], 0
	v_mfma_f32_16x16x32_bf16 v[108:111], v[156:159], v[180:183], 0
	v_mfma_f32_16x16x32_bf16 v[104:107], v[164:167], v[180:183], 0
	v_mfma_f32_16x16x32_bf16 v[92:95], v[156:159], v[188:191], 0
	v_mfma_f32_16x16x32_bf16 v[88:91], v[164:167], v[188:191], 0
	v_mfma_f32_16x16x32_bf16 v[76:79], v[156:159], v[220:223], 0
	v_mfma_f32_16x16x32_bf16 v[72:75], v[164:167], v[220:223], 0
	s_waitcnt lgkmcnt(0)
	v_mfma_f32_16x16x32_bf16 v[124:127], v[160:163], v[176:179], v[124:127]
	v_mfma_f32_16x16x32_bf16 v[120:123], v[168:171], v[176:179], v[120:123]
	v_mfma_f32_16x16x32_bf16 v[108:111], v[160:163], v[184:187], v[108:111]
	v_mfma_f32_16x16x32_bf16 v[104:107], v[168:171], v[184:187], v[104:107]
	v_mfma_f32_16x16x32_bf16 v[92:95], v[160:163], v[216:219], v[92:95]
	v_mfma_f32_16x16x32_bf16 v[88:91], v[168:171], v[216:219], v[88:91]
	v_mfma_f32_16x16x32_bf16 v[76:79], v[160:163], v[224:227], v[76:79]
	v_mfma_f32_16x16x32_bf16 v[72:75], v[168:171], v[224:227], v[72:75]
	s_setprio 0
	s_barrier
	s_add_i32 s50, 0, 0x14000
	v_add_u32_e32 v152, s50, v154
	s_add_i32 s47, s47, s29
	ds_read_b128 v[228:231], v152
	ds_read_b128 v[236:239], v152 offset:2048
	ds_read_b128 v[232:235], v152 offset:1024
	ds_read_b128 v[240:243], v152 offset:3072
	s_mov_b32 m0, s47
	s_nop 0
	global_load_lds_dwordx4 v132, s[22:23]
	s_add_i32 m0, s47, 0x2000
	s_nop 0
	global_load_lds_dwordx4 v128, s[22:23]
	s_waitcnt vmcnt(10)
	s_barrier
	s_waitcnt lgkmcnt(2)
	s_setprio 1
	v_mfma_f32_16x16x32_bf16 v[116:119], v[228:231], v[172:175], 0
	v_mfma_f32_16x16x32_bf16 v[112:115], v[236:239], v[172:175], 0
	v_mfma_f32_16x16x32_bf16 v[100:103], v[228:231], v[180:183], 0
	v_mfma_f32_16x16x32_bf16 v[96:99], v[236:239], v[180:183], 0
	v_mfma_f32_16x16x32_bf16 v[84:87], v[228:231], v[188:191], 0
	v_mfma_f32_16x16x32_bf16 v[80:83], v[236:239], v[188:191], 0
	v_mfma_f32_16x16x32_bf16 v[68:71], v[228:231], v[220:223], 0
	v_mfma_f32_16x16x32_bf16 v[64:67], v[236:239], v[220:223], 0
	s_waitcnt lgkmcnt(0)
	v_mfma_f32_16x16x32_bf16 v[116:119], v[232:235], v[176:179], v[116:119]
	v_mfma_f32_16x16x32_bf16 v[112:115], v[240:243], v[176:179], v[112:115]
	v_mfma_f32_16x16x32_bf16 v[100:103], v[232:235], v[184:187], v[100:103]
	v_mfma_f32_16x16x32_bf16 v[96:99], v[240:243], v[184:187], v[96:99]
	v_mfma_f32_16x16x32_bf16 v[84:87], v[232:235], v[216:219], v[84:87]
	v_mfma_f32_16x16x32_bf16 v[80:83], v[240:243], v[216:219], v[80:83]
	v_mfma_f32_16x16x32_bf16 v[68:71], v[232:235], v[224:227], v[68:71]
	v_mfma_f32_16x16x32_bf16 v[64:67], v[240:243], v[224:227], v[64:67]
	s_setprio 0
	s_mov_b32 m0, s17
	v_lshl_add_u64 v[246:247], s[24:25], 0, v[132:133]
	s_barrier
	ds_read_b128 v[172:175], v155 offset:16384
	ds_read_b128 v[180:183], v155 offset:18432
	ds_read_b128 v[188:191], v155 offset:20480
	ds_read_b128 v[220:223], v155 offset:22528
	ds_read_b128 v[176:179], v155 offset:17408
	ds_read_b128 v[184:187], v155 offset:19456
	ds_read_b128 v[216:219], v155 offset:21504
	ds_read_b128 v[224:227], v155 offset:23552
	global_load_lds_dwordx4 v132, s[24:25]
	v_lshl_add_u64 v[248:249], s[24:25], 0, v[128:129]
	s_mov_b32 m0, s31
	s_nop 0
	global_load_lds_dwordx4 v128, s[24:25]
	s_waitcnt vmcnt(10)
	s_barrier
	s_waitcnt lgkmcnt(4)
	s_setprio 1
	v_mfma_f32_16x16x32_bf16 v[60:63], v[156:159], v[172:175], 0
	v_mfma_f32_16x16x32_bf16 v[56:59], v[164:167], v[172:175], 0
	v_mfma_f32_16x16x32_bf16 v[44:47], v[156:159], v[180:183], 0
	v_mfma_f32_16x16x32_bf16 v[40:43], v[164:167], v[180:183], 0
	v_mfma_f32_16x16x32_bf16 v[28:31], v[156:159], v[188:191], 0
	v_mfma_f32_16x16x32_bf16 v[24:27], v[164:167], v[188:191], 0
	v_mfma_f32_16x16x32_bf16 v[12:15], v[156:159], v[220:223], 0
	v_mfma_f32_16x16x32_bf16 v[8:11], v[164:167], v[220:223], 0
	s_waitcnt lgkmcnt(0)
	v_mfma_f32_16x16x32_bf16 v[60:63], v[160:163], v[176:179], v[60:63]
	v_mfma_f32_16x16x32_bf16 v[56:59], v[168:171], v[176:179], v[56:59]
	v_mfma_f32_16x16x32_bf16 v[44:47], v[160:163], v[184:187], v[44:47]
	v_mfma_f32_16x16x32_bf16 v[40:43], v[168:171], v[184:187], v[40:43]
	v_mfma_f32_16x16x32_bf16 v[28:31], v[160:163], v[216:219], v[28:31]
	v_mfma_f32_16x16x32_bf16 v[24:27], v[168:171], v[216:219], v[24:27]
	v_mfma_f32_16x16x32_bf16 v[12:15], v[160:163], v[224:227], v[12:15]
	v_mfma_f32_16x16x32_bf16 v[8:11], v[168:171], v[224:227], v[8:11]
	s_setprio 0
	s_barrier
	s_add_u32 s48, s22, 0x40000
	s_addc_u32 s49, s23, 0
	s_add_i32 s47, s50, s29
	s_mov_b32 m0, s47
	s_nop 0
	global_load_lds_dwordx4 v132, s[48:49]
	s_add_i32 m0, s47, 0x2000
	s_nop 0
	global_load_lds_dwordx4 v128, s[48:49]
	v_add_u32_e32 v168, 0x18000, v154
	ds_read_b128 v[156:159], v168
	ds_read_b128 v[160:163], v168 offset:1024
	ds_read_b128 v[164:167], v168 offset:2048
	ds_read_b128 v[168:171], v168 offset:3072
	s_waitcnt vmcnt(10)
	s_barrier
	s_setprio 1
	v_mfma_f32_16x16x32_bf16 v[52:55], v[228:231], v[172:175], 0
	v_mfma_f32_16x16x32_bf16 v[48:51], v[236:239], v[172:175], 0
	v_mfma_f32_16x16x32_bf16 v[36:39], v[228:231], v[180:183], 0
	v_mfma_f32_16x16x32_bf16 v[32:35], v[236:239], v[180:183], 0
	v_mfma_f32_16x16x32_bf16 v[20:23], v[228:231], v[188:191], 0
	v_mfma_f32_16x16x32_bf16 v[16:19], v[236:239], v[188:191], 0
	v_mfma_f32_16x16x32_bf16 v[4:7], v[228:231], v[220:223], 0
	v_mfma_f32_16x16x32_bf16 v[0:3], v[236:239], v[220:223], 0
	v_mfma_f32_16x16x32_bf16 v[52:55], v[232:235], v[176:179], v[52:55]
	v_mfma_f32_16x16x32_bf16 v[48:51], v[240:243], v[176:179], v[48:51]
	v_mfma_f32_16x16x32_bf16 v[36:39], v[232:235], v[184:187], v[36:39]
	v_mfma_f32_16x16x32_bf16 v[32:35], v[240:243], v[184:187], v[32:35]
	v_mfma_f32_16x16x32_bf16 v[20:23], v[232:235], v[216:219], v[20:23]
	v_mfma_f32_16x16x32_bf16 v[16:19], v[240:243], v[216:219], v[16:19]
	v_mfma_f32_16x16x32_bf16 v[4:7], v[232:235], v[224:227], v[4:7]
	v_mfma_f32_16x16x32_bf16 v[0:3], v[240:243], v[224:227], v[0:3]
	s_setprio 0
	s_add_i32 s47, 0, 0x18000
	s_barrier
	s_add_u32 s24, s24, 0x40000
	s_addc_u32 s25, s25, 0
	s_mov_b32 m0, s34
	ds_read_b128 v[172:175], v155 offset:32768
	ds_read_b128 v[180:183], v155 offset:34816
	ds_read_b128 v[188:191], v155 offset:36864
	ds_read_b128 v[220:223], v155 offset:38912
	ds_read_b128 v[176:179], v155 offset:33792
	ds_read_b128 v[184:187], v155 offset:35840
	ds_read_b128 v[216:219], v155 offset:37888
	ds_read_b128 v[224:227], v155 offset:39936
	global_load_lds_dwordx4 v132, s[24:25]
	s_mov_b32 m0, s35
	s_nop 0
	global_load_lds_dwordx4 v128, s[24:25]
	s_waitcnt lgkmcnt(8)
	s_waitcnt vmcnt(10)
	s_barrier
	s_waitcnt lgkmcnt(4)
	s_setprio 1
	v_mfma_f32_16x16x32_bf16 v[124:127], v[156:159], v[172:175], v[124:127]
	v_mfma_f32_16x16x32_bf16 v[120:123], v[164:167], v[172:175], v[120:123]
	v_mfma_f32_16x16x32_bf16 v[108:111], v[156:159], v[180:183], v[108:111]
	v_mfma_f32_16x16x32_bf16 v[104:107], v[164:167], v[180:183], v[104:107]
	v_mfma_f32_16x16x32_bf16 v[92:95], v[156:159], v[188:191], v[92:95]
	v_mfma_f32_16x16x32_bf16 v[88:91], v[164:167], v[188:191], v[88:91]
	v_mfma_f32_16x16x32_bf16 v[76:79], v[156:159], v[220:223], v[76:79]
	v_mfma_f32_16x16x32_bf16 v[72:75], v[164:167], v[220:223], v[72:75]
	s_waitcnt lgkmcnt(0)
	v_mfma_f32_16x16x32_bf16 v[124:127], v[160:163], v[176:179], v[124:127]
	v_mfma_f32_16x16x32_bf16 v[120:123], v[168:171], v[176:179], v[120:123]
	v_mfma_f32_16x16x32_bf16 v[108:111], v[160:163], v[184:187], v[108:111]
	v_mfma_f32_16x16x32_bf16 v[104:107], v[168:171], v[184:187], v[104:107]
	v_mfma_f32_16x16x32_bf16 v[92:95], v[160:163], v[216:219], v[92:95]
	v_mfma_f32_16x16x32_bf16 v[88:91], v[168:171], v[216:219], v[88:91]
	v_mfma_f32_16x16x32_bf16 v[76:79], v[160:163], v[224:227], v[76:79]
	v_mfma_f32_16x16x32_bf16 v[72:75], v[168:171], v[224:227], v[72:75]
	s_setprio 0
	s_barrier
	s_add_i32 s24, 0, 0x1c000
	s_add_i32 s25, s47, s29
	v_add_u32_e32 v200, s24, v154
	s_mov_b32 m0, s25
	ds_read_b128 v[228:231], v200
	ds_read_b128 v[236:239], v200 offset:2048
	ds_read_b128 v[232:235], v200 offset:1024
	ds_read_b128 v[240:243], v200 offset:3072
	s_add_u32 s98, s22, 0x80
	s_addc_u32 s99, s23, 0
	global_load_lds_dwordx4 v132, s[98:99]
	s_add_i32 m0, s25, 0x2000
	s_nop 0
	global_load_lds_dwordx4 v128, s[98:99]
	s_waitcnt vmcnt(10)
	s_barrier
	s_waitcnt lgkmcnt(2)
	s_setprio 1
	v_mfma_f32_16x16x32_bf16 v[116:119], v[228:231], v[172:175], v[116:119]
	v_mfma_f32_16x16x32_bf16 v[112:115], v[236:239], v[172:175], v[112:115]
	v_mfma_f32_16x16x32_bf16 v[100:103], v[228:231], v[180:183], v[100:103]
	v_mfma_f32_16x16x32_bf16 v[96:99], v[236:239], v[180:183], v[96:99]
	v_mfma_f32_16x16x32_bf16 v[84:87], v[228:231], v[188:191], v[84:87]
	v_mfma_f32_16x16x32_bf16 v[80:83], v[236:239], v[188:191], v[80:83]
	v_mfma_f32_16x16x32_bf16 v[68:71], v[228:231], v[220:223], v[68:71]
	v_mfma_f32_16x16x32_bf16 v[64:67], v[236:239], v[220:223], v[64:67]
	s_waitcnt lgkmcnt(0)
	v_mfma_f32_16x16x32_bf16 v[116:119], v[232:235], v[176:179], v[116:119]
	v_mfma_f32_16x16x32_bf16 v[112:115], v[240:243], v[176:179], v[112:115]
	v_mfma_f32_16x16x32_bf16 v[100:103], v[232:235], v[184:187], v[100:103]
	v_mfma_f32_16x16x32_bf16 v[96:99], v[240:243], v[184:187], v[96:99]
	v_mfma_f32_16x16x32_bf16 v[84:87], v[232:235], v[216:219], v[84:87]
	v_mfma_f32_16x16x32_bf16 v[80:83], v[240:243], v[216:219], v[80:83]
	v_mfma_f32_16x16x32_bf16 v[68:71], v[232:235], v[224:227], v[68:71]
	v_mfma_f32_16x16x32_bf16 v[64:67], v[240:243], v[224:227], v[64:67]
	s_setprio 0
	s_mov_b32 m0, s36
	v_lshl_add_u64 v[152:153], v[246:247], 0, s[66:67]
	s_barrier
	ds_read_b128 v[172:175], v155 offset:49152
	ds_read_b128 v[180:183], v155 offset:51200
	ds_read_b128 v[188:191], v155 offset:53248
	ds_read_b128 v[220:223], v155 offset:55296
	ds_read_b128 v[176:179], v155 offset:50176
	ds_read_b128 v[184:187], v155 offset:52224
	ds_read_b128 v[216:219], v155 offset:54272
	ds_read_b128 v[224:227], v155 offset:56320
	global_load_lds_dwordx4 v[152:153], off
	v_lshl_add_u64 v[152:153], v[248:249], 0, s[66:67]
	s_mov_b32 m0, s37
	s_nop 0
	global_load_lds_dwordx4 v[152:153], off
	s_waitcnt vmcnt(10)
	s_barrier
	s_waitcnt lgkmcnt(4)
	s_setprio 1
	v_mfma_f32_16x16x32_bf16 v[60:63], v[156:159], v[172:175], v[60:63]
	v_mfma_f32_16x16x32_bf16 v[56:59], v[164:167], v[172:175], v[56:59]
	v_mfma_f32_16x16x32_bf16 v[44:47], v[156:159], v[180:183], v[44:47]
	v_mfma_f32_16x16x32_bf16 v[40:43], v[164:167], v[180:183], v[40:43]
	v_mfma_f32_16x16x32_bf16 v[28:31], v[156:159], v[188:191], v[28:31]
	v_mfma_f32_16x16x32_bf16 v[24:27], v[164:167], v[188:191], v[24:27]
	v_mfma_f32_16x16x32_bf16 v[12:15], v[156:159], v[220:223], v[12:15]
	v_mfma_f32_16x16x32_bf16 v[8:11], v[164:167], v[220:223], v[8:11]
	s_waitcnt lgkmcnt(0)
	v_mfma_f32_16x16x32_bf16 v[60:63], v[160:163], v[176:179], v[60:63]
	v_mfma_f32_16x16x32_bf16 v[56:59], v[168:171], v[176:179], v[56:59]
	v_mfma_f32_16x16x32_bf16 v[44:47], v[160:163], v[184:187], v[44:47]
	v_mfma_f32_16x16x32_bf16 v[40:43], v[168:171], v[184:187], v[40:43]
	v_mfma_f32_16x16x32_bf16 v[28:31], v[160:163], v[216:219], v[28:31]
	v_mfma_f32_16x16x32_bf16 v[24:27], v[168:171], v[216:219], v[24:27]
	v_mfma_f32_16x16x32_bf16 v[12:15], v[160:163], v[224:227], v[12:15]
	v_mfma_f32_16x16x32_bf16 v[8:11], v[168:171], v[224:227], v[8:11]
	s_setprio 0
	s_barrier
	s_add_u32 s22, s22, 0x40080
	s_addc_u32 s23, s23, 0
	s_add_i32 s24, s24, s29
	s_mov_b32 m0, s24
	s_nop 0
	global_load_lds_dwordx4 v132, s[22:23]
	s_add_i32 m0, s24, 0x2000
	s_nop 0
	global_load_lds_dwordx4 v128, s[22:23]
	v_add_u32_e32 v168, 0x10000, v154
	ds_read_b128 v[156:159], v168
	ds_read_b128 v[160:163], v168 offset:1024
	ds_read_b128 v[164:167], v168 offset:2048
	ds_read_b128 v[168:171], v168 offset:3072
	s_waitcnt vmcnt(10)
	s_barrier
	s_setprio 1
	v_mfma_f32_16x16x32_bf16 v[52:55], v[228:231], v[172:175], v[52:55]
	v_mfma_f32_16x16x32_bf16 v[48:51], v[236:239], v[172:175], v[48:51]
	v_mfma_f32_16x16x32_bf16 v[36:39], v[228:231], v[180:183], v[36:39]
	v_mfma_f32_16x16x32_bf16 v[32:35], v[236:239], v[180:183], v[32:35]
	v_mfma_f32_16x16x32_bf16 v[20:23], v[228:231], v[188:191], v[20:23]
	v_mfma_f32_16x16x32_bf16 v[16:19], v[236:239], v[188:191], v[16:19]
	v_mfma_f32_16x16x32_bf16 v[4:7], v[228:231], v[220:223], v[4:7]
	v_mfma_f32_16x16x32_bf16 v[0:3], v[236:239], v[220:223], v[0:3]
	v_mfma_f32_16x16x32_bf16 v[52:55], v[232:235], v[176:179], v[52:55]
	v_mfma_f32_16x16x32_bf16 v[48:51], v[240:243], v[176:179], v[48:51]
	v_mfma_f32_16x16x32_bf16 v[36:39], v[232:235], v[184:187], v[36:39]
	v_mfma_f32_16x16x32_bf16 v[32:35], v[240:243], v[184:187], v[32:35]
	v_mfma_f32_16x16x32_bf16 v[20:23], v[232:235], v[216:219], v[20:23]
	v_mfma_f32_16x16x32_bf16 v[16:19], v[240:243], v[216:219], v[16:19]
	v_mfma_f32_16x16x32_bf16 v[4:7], v[232:235], v[224:227], v[4:7]
	v_mfma_f32_16x16x32_bf16 v[0:3], v[240:243], v[224:227], v[0:3]
	s_setprio 0
	s_add_i32 s46, s46, 2
	s_add_u32 s18, s18, 0x100
	s_addc_u32 s19, s19, 0
	s_add_u32 s44, s44, 0x100
	s_addc_u32 s45, s45, 0
	s_cmp_gt_u32 s46, 13
	s_barrier

.LBB0_1233:
	s_add_u32 s8, s12, 0x80
	s_addc_u32 s9, s13, 0
	s_add_u32 s38, s10, 0x100
	s_addc_u32 s39, s11, 0
	s_mov_b32 s10, 0
	v_add_u32_e32 v168, 0x10000, v154
	ds_read_b128 v[156:159], v168
	ds_read_b128 v[160:163], v168 offset:1024
	ds_read_b128 v[164:167], v168 offset:2048
	ds_read_b128 v[168:171], v168 offset:3072
	s_add_i32 s40, s10, 2
	s_add_u32 s12, s8, 0x80
	s_addc_u32 s11, s9, 0
	s_add_i32 s41, 0, 0x10000
	s_cmp_eq_u32 s29, s10
	s_cselect_b32 s10, s2, s12
	s_cselect_b32 s11, s3, s11
	s_cselect_b32 s13, s7, s39
	s_cselect_b32 s12, s6, s38
	s_add_i32 m0, s22, 0xc000
	ds_read_b128 v[172:175], v155
	ds_read_b128 v[180:183], v155 offset:2048
	ds_read_b128 v[188:191], v155 offset:4096
	ds_read_b128 v[220:223], v155 offset:6144
	ds_read_b128 v[176:179], v155 offset:1024
	ds_read_b128 v[184:187], v155 offset:3072
	ds_read_b128 v[216:219], v155 offset:5120
	ds_read_b128 v[224:227], v155 offset:7168
	global_load_lds_dwordx4 v130, s[8:9]
	s_add_i32 m0, s22, 0xe000
	s_nop 0
	global_load_lds_dwordx4 v150, s[8:9]
	s_waitcnt lgkmcnt(8)
	s_waitcnt vmcnt(10)
	s_barrier
	s_waitcnt lgkmcnt(4)
	s_setprio 1
	v_mfma_f32_16x16x32_bf16 v[124:127], v[156:159], v[172:175], 0
	v_mfma_f32_16x16x32_bf16 v[120:123], v[164:167], v[172:175], 0
	v_mfma_f32_16x16x32_bf16 v[116:119], v[156:159], v[180:183], 0
	v_mfma_f32_16x16x32_bf16 v[108:111], v[164:167], v[180:183], 0
	v_mfma_f32_16x16x32_bf16 v[100:103], v[156:159], v[188:191], 0
	v_mfma_f32_16x16x32_bf16 v[92:95], v[164:167], v[188:191], 0
	v_mfma_f32_16x16x32_bf16 v[84:87], v[156:159], v[220:223], 0
	v_mfma_f32_16x16x32_bf16 v[76:79], v[164:167], v[220:223], 0
	s_waitcnt lgkmcnt(0)
	v_mfma_f32_16x16x32_bf16 v[124:127], v[160:163], v[176:179], v[124:127]
	v_mfma_f32_16x16x32_bf16 v[120:123], v[168:171], v[176:179], v[120:123]
	v_mfma_f32_16x16x32_bf16 v[116:119], v[160:163], v[184:187], v[116:119]
	v_mfma_f32_16x16x32_bf16 v[108:111], v[168:171], v[184:187], v[108:111]
	v_mfma_f32_16x16x32_bf16 v[100:103], v[160:163], v[216:219], v[100:103]
	v_mfma_f32_16x16x32_bf16 v[92:95], v[168:171], v[216:219], v[92:95]
	v_mfma_f32_16x16x32_bf16 v[84:87], v[160:163], v[224:227], v[84:87]
	v_mfma_f32_16x16x32_bf16 v[76:79], v[168:171], v[224:227], v[76:79]
	s_setprio 0
	s_barrier
	s_add_i32 s42, 0, 0x14000
	v_add_u32_e32 v152, s42, v154
	s_add_i32 s41, s41, s19
	ds_read_b128 v[228:231], v152
	ds_read_b128 v[236:239], v152 offset:2048
	ds_read_b128 v[232:235], v152 offset:1024
	ds_read_b128 v[240:243], v152 offset:3072
	v_lshl_add_u64 v[152:153], s[12:13], 0, v[132:133]
	s_mov_b32 m0, s41
	v_lshl_add_u64 v[244:245], s[12:13], 0, v[128:129]
	global_load_lds_dwordx4 v132, s[12:13]
	s_add_i32 m0, s41, 0x2000
	s_nop 0
	global_load_lds_dwordx4 v128, s[12:13]
	s_waitcnt vmcnt(10)
	s_barrier
	s_waitcnt lgkmcnt(2)
	s_setprio 1
	v_mfma_f32_16x16x32_bf16 v[112:115], v[228:231], v[172:175], 0
	v_mfma_f32_16x16x32_bf16 v[104:107], v[236:239], v[172:175], 0
	v_mfma_f32_16x16x32_bf16 v[96:99], v[228:231], v[180:183], 0
	v_mfma_f32_16x16x32_bf16 v[88:91], v[236:239], v[180:183], 0
	v_mfma_f32_16x16x32_bf16 v[80:83], v[228:231], v[188:191], 0
	v_mfma_f32_16x16x32_bf16 v[72:75], v[236:239], v[188:191], 0
	v_mfma_f32_16x16x32_bf16 v[68:71], v[228:231], v[220:223], 0
	v_mfma_f32_16x16x32_bf16 v[64:67], v[236:239], v[220:223], 0
	s_waitcnt lgkmcnt(0)
	v_mfma_f32_16x16x32_bf16 v[112:115], v[232:235], v[176:179], v[112:115]
	v_mfma_f32_16x16x32_bf16 v[104:107], v[240:243], v[176:179], v[104:107]
	v_mfma_f32_16x16x32_bf16 v[96:99], v[232:235], v[184:187], v[96:99]
	v_mfma_f32_16x16x32_bf16 v[88:91], v[240:243], v[184:187], v[88:91]
	v_mfma_f32_16x16x32_bf16 v[80:83], v[232:235], v[216:219], v[80:83]
	v_mfma_f32_16x16x32_bf16 v[72:75], v[240:243], v[216:219], v[72:75]
	v_mfma_f32_16x16x32_bf16 v[68:71], v[232:235], v[224:227], v[68:71]
	v_mfma_f32_16x16x32_bf16 v[64:67], v[240:243], v[224:227], v[64:67]
	s_setprio 0
	s_mov_b32 m0, s22
	v_lshl_add_u64 v[246:247], s[10:11], 0, v[132:133]
	s_barrier
	ds_read_b128 v[172:175], v155 offset:16384
	ds_read_b128 v[180:183], v155 offset:18432
	ds_read_b128 v[188:191], v155 offset:20480
	ds_read_b128 v[220:223], v155 offset:22528
	ds_read_b128 v[176:179], v155 offset:17408
	ds_read_b128 v[184:187], v155 offset:19456
	ds_read_b128 v[216:219], v155 offset:21504
	ds_read_b128 v[224:227], v155 offset:23552
	global_load_lds_dwordx4 v132, s[10:11]
	v_lshl_add_u64 v[248:249], s[10:11], 0, v[128:129]
	s_mov_b32 m0, s23
	s_nop 0
	global_load_lds_dwordx4 v128, s[10:11]
	s_waitcnt vmcnt(10)
	s_barrier
	s_waitcnt lgkmcnt(4)
	s_setprio 1
	v_mfma_f32_16x16x32_bf16 v[60:63], v[156:159], v[172:175], 0
	v_mfma_f32_16x16x32_bf16 v[56:59], v[164:167], v[172:175], 0
	v_mfma_f32_16x16x32_bf16 v[52:55], v[156:159], v[180:183], 0
	v_mfma_f32_16x16x32_bf16 v[44:47], v[164:167], v[180:183], 0
	v_mfma_f32_16x16x32_bf16 v[36:39], v[156:159], v[188:191], 0
	v_mfma_f32_16x16x32_bf16 v[28:31], v[164:167], v[188:191], 0
	v_mfma_f32_16x16x32_bf16 v[20:23], v[156:159], v[220:223], 0
	v_mfma_f32_16x16x32_bf16 v[12:15], v[164:167], v[220:223], 0
	s_waitcnt lgkmcnt(0)
	v_mfma_f32_16x16x32_bf16 v[60:63], v[160:163], v[176:179], v[60:63]
	v_mfma_f32_16x16x32_bf16 v[56:59], v[168:171], v[176:179], v[56:59]
	v_mfma_f32_16x16x32_bf16 v[52:55], v[160:163], v[184:187], v[52:55]
	v_mfma_f32_16x16x32_bf16 v[44:47], v[168:171], v[184:187], v[44:47]
	v_mfma_f32_16x16x32_bf16 v[36:39], v[160:163], v[216:219], v[36:39]
	v_mfma_f32_16x16x32_bf16 v[28:31], v[168:171], v[216:219], v[28:31]
	v_mfma_f32_16x16x32_bf16 v[20:23], v[160:163], v[224:227], v[20:23]
	v_mfma_f32_16x16x32_bf16 v[12:15], v[168:171], v[224:227], v[12:15]
	s_setprio 0
	s_barrier
	s_add_u32 s12, s12, s58
	s_addc_u32 s13, s13, 0
	s_add_i32 s41, s42, s19
	v_lshl_add_u64 v[250:251], s[12:13], 0, v[132:133]
	s_mov_b32 m0, s41
	v_lshl_add_u64 v[252:253], s[12:13], 0, v[128:129]
	global_load_lds_dwordx4 v132, s[12:13]
	s_add_i32 m0, s41, 0x2000
	s_nop 0
	global_load_lds_dwordx4 v128, s[12:13]
	v_add_u32_e32 v168, 0x18000, v154
	ds_read_b128 v[156:159], v168
	ds_read_b128 v[160:163], v168 offset:1024
	ds_read_b128 v[164:167], v168 offset:2048
	ds_read_b128 v[168:171], v168 offset:3072
	s_waitcnt vmcnt(10)
	s_barrier
	s_setprio 1
	v_mfma_f32_16x16x32_bf16 v[48:51], v[228:231], v[172:175], 0
	v_mfma_f32_16x16x32_bf16 v[40:43], v[236:239], v[172:175], 0
	v_mfma_f32_16x16x32_bf16 v[32:35], v[228:231], v[180:183], 0
	v_mfma_f32_16x16x32_bf16 v[24:27], v[236:239], v[180:183], 0
	v_mfma_f32_16x16x32_bf16 v[16:19], v[228:231], v[188:191], 0
	v_mfma_f32_16x16x32_bf16 v[8:11], v[236:239], v[188:191], 0
	v_mfma_f32_16x16x32_bf16 v[4:7], v[228:231], v[220:223], 0
	v_mfma_f32_16x16x32_bf16 v[0:3], v[236:239], v[220:223], 0
	v_mfma_f32_16x16x32_bf16 v[48:51], v[232:235], v[176:179], v[48:51]
	v_mfma_f32_16x16x32_bf16 v[40:43], v[240:243], v[176:179], v[40:43]
	v_mfma_f32_16x16x32_bf16 v[32:35], v[232:235], v[184:187], v[32:35]
	v_mfma_f32_16x16x32_bf16 v[24:27], v[240:243], v[184:187], v[24:27]
	v_mfma_f32_16x16x32_bf16 v[16:19], v[232:235], v[216:219], v[16:19]
	v_mfma_f32_16x16x32_bf16 v[8:11], v[240:243], v[216:219], v[8:11]
	v_mfma_f32_16x16x32_bf16 v[4:7], v[232:235], v[224:227], v[4:7]
	v_mfma_f32_16x16x32_bf16 v[0:3], v[240:243], v[224:227], v[0:3]
	s_setprio 0
	s_add_i32 s12, 0, 0x18000
	s_barrier
	s_add_u32 s10, s10, s58
	s_addc_u32 s11, s11, 0
	s_mov_b32 m0, s24
	ds_read_b128 v[172:175], v155 offset:32768
	ds_read_b128 v[180:183], v155 offset:34816
	ds_read_b128 v[188:191], v155 offset:36864
	ds_read_b128 v[220:223], v155 offset:38912
	ds_read_b128 v[176:179], v155 offset:33792
	ds_read_b128 v[184:187], v155 offset:35840
	ds_read_b128 v[216:219], v155 offset:37888
	ds_read_b128 v[224:227], v155 offset:39936
	global_load_lds_dwordx4 v132, s[10:11]
	s_mov_b32 m0, s25
	s_nop 0
	global_load_lds_dwordx4 v128, s[10:11]
	s_waitcnt lgkmcnt(8)
	s_waitcnt vmcnt(10)
	s_barrier
	s_waitcnt lgkmcnt(4)
	s_setprio 1
	v_mfma_f32_16x16x32_bf16 v[124:127], v[156:159], v[172:175], v[124:127]
	v_mfma_f32_16x16x32_bf16 v[120:123], v[164:167], v[172:175], v[120:123]
	v_mfma_f32_16x16x32_bf16 v[116:119], v[156:159], v[180:183], v[116:119]
	v_mfma_f32_16x16x32_bf16 v[108:111], v[164:167], v[180:183], v[108:111]
	v_mfma_f32_16x16x32_bf16 v[100:103], v[156:159], v[188:191], v[100:103]
	v_mfma_f32_16x16x32_bf16 v[92:95], v[164:167], v[188:191], v[92:95]
	v_mfma_f32_16x16x32_bf16 v[84:87], v[156:159], v[220:223], v[84:87]
	v_mfma_f32_16x16x32_bf16 v[76:79], v[164:167], v[220:223], v[76:79]
	s_waitcnt lgkmcnt(0)
	v_mfma_f32_16x16x32_bf16 v[124:127], v[160:163], v[176:179], v[124:127]
	v_mfma_f32_16x16x32_bf16 v[120:123], v[168:171], v[176:179], v[120:123]
	v_mfma_f32_16x16x32_bf16 v[116:119], v[160:163], v[184:187], v[116:119]
	v_mfma_f32_16x16x32_bf16 v[108:111], v[168:171], v[184:187], v[108:111]
	v_mfma_f32_16x16x32_bf16 v[100:103], v[160:163], v[216:219], v[100:103]
	v_mfma_f32_16x16x32_bf16 v[92:95], v[168:171], v[216:219], v[92:95]
	v_mfma_f32_16x16x32_bf16 v[84:87], v[160:163], v[224:227], v[84:87]
	v_mfma_f32_16x16x32_bf16 v[76:79], v[168:171], v[224:227], v[76:79]
	s_setprio 0
	s_barrier
	s_add_i32 s10, 0, 0x1c000
	s_add_i32 s11, s12, s19
	v_add_u32_e32 v200, s10, v154
	v_lshl_add_u64 v[152:153], v[152:153], 0, s[66:67]
	s_mov_b32 m0, s11
	ds_read_b128 v[228:231], v200
	ds_read_b128 v[236:239], v200 offset:2048
	ds_read_b128 v[232:235], v200 offset:1024
	ds_read_b128 v[240:243], v200 offset:3072
	global_load_lds_dwordx4 v[152:153], off
	v_lshl_add_u64 v[152:153], v[244:245], 0, s[66:67]
	s_add_i32 m0, s11, 0x2000
	s_nop 0
	global_load_lds_dwordx4 v[152:153], off
	s_waitcnt vmcnt(10)
	s_barrier
	s_waitcnt lgkmcnt(2)
	s_setprio 1
	v_mfma_f32_16x16x32_bf16 v[112:115], v[228:231], v[172:175], v[112:115]
	v_mfma_f32_16x16x32_bf16 v[104:107], v[236:239], v[172:175], v[104:107]
	v_mfma_f32_16x16x32_bf16 v[96:99], v[228:231], v[180:183], v[96:99]
	v_mfma_f32_16x16x32_bf16 v[88:91], v[236:239], v[180:183], v[88:91]
	v_mfma_f32_16x16x32_bf16 v[80:83], v[228:231], v[188:191], v[80:83]
	v_mfma_f32_16x16x32_bf16 v[72:75], v[236:239], v[188:191], v[72:75]
	v_mfma_f32_16x16x32_bf16 v[68:71], v[228:231], v[220:223], v[68:71]
	v_mfma_f32_16x16x32_bf16 v[64:67], v[236:239], v[220:223], v[64:67]
	s_waitcnt lgkmcnt(0)
	v_mfma_f32_16x16x32_bf16 v[112:115], v[232:235], v[176:179], v[112:115]
	v_mfma_f32_16x16x32_bf16 v[104:107], v[240:243], v[176:179], v[104:107]
	v_mfma_f32_16x16x32_bf16 v[96:99], v[232:235], v[184:187], v[96:99]
	v_mfma_f32_16x16x32_bf16 v[88:91], v[240:243], v[184:187], v[88:91]
	v_mfma_f32_16x16x32_bf16 v[80:83], v[232:235], v[216:219], v[80:83]
	v_mfma_f32_16x16x32_bf16 v[72:75], v[240:243], v[216:219], v[72:75]
	v_mfma_f32_16x16x32_bf16 v[68:71], v[232:235], v[224:227], v[68:71]
	v_mfma_f32_16x16x32_bf16 v[64:67], v[240:243], v[224:227], v[64:67]
	s_setprio 0
	s_mov_b32 m0, s26
	v_lshl_add_u64 v[152:153], v[246:247], 0, s[66:67]
	s_barrier
	ds_read_b128 v[172:175], v155 offset:49152
	ds_read_b128 v[180:183], v155 offset:51200
	ds_read_b128 v[188:191], v155 offset:53248
	ds_read_b128 v[220:223], v155 offset:55296
	ds_read_b128 v[176:179], v155 offset:50176
	ds_read_b128 v[184:187], v155 offset:52224
	ds_read_b128 v[216:219], v155 offset:54272
	ds_read_b128 v[224:227], v155 offset:56320
	global_load_lds_dwordx4 v[152:153], off
	v_lshl_add_u64 v[152:153], v[248:249], 0, s[66:67]
	s_mov_b32 m0, s27
	s_nop 0
	global_load_lds_dwordx4 v[152:153], off
	s_waitcnt vmcnt(10)
	s_barrier
	s_waitcnt lgkmcnt(4)
	s_setprio 1
	v_mfma_f32_16x16x32_bf16 v[60:63], v[156:159], v[172:175], v[60:63]
	v_mfma_f32_16x16x32_bf16 v[56:59], v[164:167], v[172:175], v[56:59]
	v_mfma_f32_16x16x32_bf16 v[52:55], v[156:159], v[180:183], v[52:55]
	v_mfma_f32_16x16x32_bf16 v[44:47], v[164:167], v[180:183], v[44:47]
	v_mfma_f32_16x16x32_bf16 v[36:39], v[156:159], v[188:191], v[36:39]
	v_mfma_f32_16x16x32_bf16 v[28:31], v[164:167], v[188:191], v[28:31]
	v_mfma_f32_16x16x32_bf16 v[20:23], v[156:159], v[220:223], v[20:23]
	v_mfma_f32_16x16x32_bf16 v[12:15], v[164:167], v[220:223], v[12:15]
	s_waitcnt lgkmcnt(0)
	v_mfma_f32_16x16x32_bf16 v[60:63], v[160:163], v[176:179], v[60:63]
	v_mfma_f32_16x16x32_bf16 v[56:59], v[168:171], v[176:179], v[56:59]
	v_mfma_f32_16x16x32_bf16 v[52:55], v[160:163], v[184:187], v[52:55]
	v_mfma_f32_16x16x32_bf16 v[44:47], v[168:171], v[184:187], v[44:47]
	v_mfma_f32_16x16x32_bf16 v[36:39], v[160:163], v[216:219], v[36:39]
	v_mfma_f32_16x16x32_bf16 v[28:31], v[168:171], v[216:219], v[28:31]
	v_mfma_f32_16x16x32_bf16 v[20:23], v[160:163], v[224:227], v[20:23]
	v_mfma_f32_16x16x32_bf16 v[12:15], v[168:171], v[224:227], v[12:15]
	s_setprio 0
	s_barrier
	s_add_i32 s10, s10, s19
	v_lshl_add_u64 v[152:153], v[250:251], 0, s[66:67]
	s_mov_b32 m0, s10
	s_nop 0
	global_load_lds_dwordx4 v[152:153], off
	v_lshl_add_u64 v[152:153], v[252:253], 0, s[66:67]
	s_add_i32 m0, s10, 0x2000
	s_nop 0
	global_load_lds_dwordx4 v[152:153], off
	v_add_u32_e32 v168, 0x10000, v154
	ds_read_b128 v[156:159], v168
	ds_read_b128 v[160:163], v168 offset:1024
	ds_read_b128 v[164:167], v168 offset:2048
	ds_read_b128 v[168:171], v168 offset:3072
	s_waitcnt vmcnt(10)
	s_barrier
	s_setprio 1
	v_mfma_f32_16x16x32_bf16 v[48:51], v[228:231], v[172:175], v[48:51]
	v_mfma_f32_16x16x32_bf16 v[40:43], v[236:239], v[172:175], v[40:43]
	v_mfma_f32_16x16x32_bf16 v[32:35], v[228:231], v[180:183], v[32:35]
	v_mfma_f32_16x16x32_bf16 v[24:27], v[236:239], v[180:183], v[24:27]
	v_mfma_f32_16x16x32_bf16 v[16:19], v[228:231], v[188:191], v[16:19]
	v_mfma_f32_16x16x32_bf16 v[8:11], v[236:239], v[188:191], v[8:11]
	v_mfma_f32_16x16x32_bf16 v[4:7], v[228:231], v[220:223], v[4:7]
	v_mfma_f32_16x16x32_bf16 v[0:3], v[236:239], v[220:223], v[0:3]
	v_mfma_f32_16x16x32_bf16 v[48:51], v[232:235], v[176:179], v[48:51]
	v_mfma_f32_16x16x32_bf16 v[40:43], v[240:243], v[176:179], v[40:43]
	v_mfma_f32_16x16x32_bf16 v[32:35], v[232:235], v[184:187], v[32:35]
	v_mfma_f32_16x16x32_bf16 v[24:27], v[240:243], v[184:187], v[24:27]
	v_mfma_f32_16x16x32_bf16 v[16:19], v[232:235], v[216:219], v[16:19]
	v_mfma_f32_16x16x32_bf16 v[8:11], v[240:243], v[216:219], v[8:11]
	v_mfma_f32_16x16x32_bf16 v[4:7], v[232:235], v[224:227], v[4:7]
	v_mfma_f32_16x16x32_bf16 v[0:3], v[240:243], v[224:227], v[0:3]
	s_setprio 0
	s_add_u32 s8, s8, 0x100
	s_addc_u32 s9, s9, 0
	s_add_u32 s38, s38, 0x100
	s_addc_u32 s39, s39, 0
	s_cmp_ge_u32 s40, s28
	s_mov_b32 s10, s40
	s_barrier
